# ffn_fixup rewritten by hand: 352 threads x one 8-column group, all 56 x4 loads of the 4 row blocks in flight at once, staged vmcnt waits, packed f32 math, same op order
# baseline (speedup 1.0000x reference)
; #define GAS __attribute__((address_space(1)))
; __device__ __forceinline__ int opq_tid() { int t = threadIdx.x; asm volatile("" : "+v"(t)); return t; }
; __device__ __forceinline__ void ffn_fixup(GAS bf16_t* __restrict__ act, const GAS float* __restrict__ SG, const GAS float* __restrict__ SU, const GAS float* __restrict__ cw, const GAS float* __restrict__ cb, int pm) {
;     constexpr int NCG = FFN / 8;
; #pragma unroll 3
;     for (int it = opq_tid(); it < 8 * NCG; it += 512) {
;         const int bq = it / (2 * NCG), rem = it - bq * 2 * NCG, rr = rem / NCG, f0 = (rem - rr * NCG) * 8;
;         const int blk64 = pm * 4 + bq, row = blk64 * 64 + rr;
;         const bool first = ((blk64 * 64) & (SEQ - 1)) == 0;
;         const GAS float* c0 = SG + ((size_t)blk64 * 4) * FFN + f0;
;         const GAS float* pv = SG + ((size_t)(blk64 - 1) * 4 + 2) * FFN + f0;
;         float gm2[8], gm1[8], gc[8], up[8];
; #pragma unroll
;         for (int e = 0; e < 8; ++e) { gm2[e] = 0.f; gm1[e] = 0.f; }
;         if (rr == 0) {
;             if (!first) { const f32x4 a = *(const GAS f32x4*)pv, b = *(const GAS f32x4*)(pv + 4), c = *(const GAS f32x4*)(pv + FFN), d = *(const GAS f32x4*)(pv + FFN + 4);
; #pragma unroll
;                 for (int e = 0; e < 4; ++e) { gm2[e] = a[e]; gm2[4 + e] = b[e]; gm1[e] = c[e]; gm1[4 + e] = d[e]; } }
;             const f32x4 a = *(const GAS f32x4*)c0, b = *(const GAS f32x4*)(c0 + 4);
; #pragma unroll
;             for (int e = 0; e < 4; ++e) { gc[e] = a[e]; gc[4 + e] = b[e]; }
;         } else {
;             if (!first) { const f32x4 c = *(const GAS f32x4*)(pv + FFN), d = *(const GAS f32x4*)(pv + FFN + 4);
; #pragma unroll
;                 for (int e = 0; e < 4; ++e) { gm2[e] = c[e]; gm2[4 + e] = d[e]; } }
;             const f32x4 a = *(const GAS f32x4*)c0, b = *(const GAS f32x4*)(c0 + 4), c = *(const GAS f32x4*)(c0 + FFN), d = *(const GAS f32x4*)(c0 + FFN + 4);
; #pragma unroll
;             for (int e = 0; e < 4; ++e) { gm1[e] = a[e]; gm1[4 + e] = b[e]; gc[e] = c[e]; gc[4 + e] = d[e]; }
;         }
;         { const GAS float* su = SU + ((size_t)blk64 * 2 + rr) * FFN + f0; const f32x4 a = *(const GAS f32x4*)su, b = *(const GAS f32x4*)(su + 4);
; #pragma unroll
;           for (int e = 0; e < 4; ++e) { up[e] = a[e]; up[4 + e] = b[e]; } }
.LBB0_130:
	v_mov_b64_e32 v[2:3], 0x100
	v_cmp_lt_i64_e32 vcc, s[2:3], v[2:3]
	s_mov_b64 s[2:3], -1
	s_cbranch_vccz .LBB0_123
	v_cmp_gt_u32_e32 vcc, 0x160, v242
	s_and_saveexec_b64 s[16:17], vcc
	s_cbranch_execz .LBB0_122
	s_add_u32 s18, s92, 0xcef5000
	s_addc_u32 s19, s93, 0
	s_add_u32 s20, s92, 0x18f00000
	s_addc_u32 s21, s93, 0
	s_lshl_b32 s36, s48, 2
	v_lshlrev_b32_e32 v1, 5, v242
	v_add_u32_e32 v232, 0x2c00, v1
	v_add_u32_e32 v233, 0x5800, v1
	global_load_dwordx4 v[2:5], v1, s[12:13]
	global_load_dwordx4 v[6:9], v1, s[12:13] offset:16
	global_load_dwordx4 v[10:13], v232, s[12:13]
	global_load_dwordx4 v[14:17], v232, s[12:13] offset:16
	global_load_dwordx4 v[18:21], v233, s[12:13]
	global_load_dwordx4 v[22:25], v233, s[12:13] offset:16
	global_load_dwordx4 v[26:29], v1, s[14:15]
	global_load_dwordx4 v[30:33], v1, s[14:15] offset:16
	s_add_i32 s22, s36, 1
	s_mul_i32 s22, s22, 0xb000
	s_add_i32 s23, s22, 0xffffa800
	s_add_i32 s24, s22, 0xffffd400
	s_add_i32 s25, s22, 0x2c00
	s_add_i32 s26, s36, 0
	s_mul_i32 s26, s26, 0x5800
	s_add_i32 s26, s26, 0x100b000
	s_add_i32 s27, s26, 0x2c00
	v_add_u32_e32 v232, s23, v1
	v_add_u32_e32 v233, s24, v1
	v_add_u32_e32 v234, s22, v1
	v_add_u32_e32 v235, s25, v1
	v_add_u32_e32 v236, s26, v1
	v_add_u32_e32 v237, s27, v1
	global_load_dwordx4 v[34:37], v232, s[18:19]
	global_load_dwordx4 v[38:41], v232, s[18:19] offset:16
	global_load_dwordx4 v[42:45], v233, s[18:19]
	global_load_dwordx4 v[46:49], v233, s[18:19] offset:16
	global_load_dwordx4 v[50:53], v234, s[18:19]
	global_load_dwordx4 v[54:57], v234, s[18:19] offset:16
	global_load_dwordx4 v[58:61], v235, s[18:19]
	global_load_dwordx4 v[62:65], v235, s[18:19] offset:16
	global_load_dwordx4 v[66:69], v236, s[18:19]
	global_load_dwordx4 v[70:73], v236, s[18:19] offset:16
	global_load_dwordx4 v[74:77], v237, s[18:19]
	global_load_dwordx4 v[78:81], v237, s[18:19] offset:16
	s_add_i32 s22, s36, 2
	s_mul_i32 s22, s22, 0xb000
	s_add_i32 s23, s22, 0xffffa800
	s_add_i32 s24, s22, 0xffffd400
	s_add_i32 s25, s22, 0x2c00
	s_add_i32 s26, s36, 1
	s_mul_i32 s26, s26, 0x5800
	s_add_i32 s26, s26, 0x100b000
	s_add_i32 s27, s26, 0x2c00
	v_add_u32_e32 v232, s23, v1
	v_add_u32_e32 v233, s24, v1
	v_add_u32_e32 v234, s22, v1
	v_add_u32_e32 v235, s25, v1
	v_add_u32_e32 v236, s26, v1
	v_add_u32_e32 v237, s27, v1
	global_load_dwordx4 v[82:85], v232, s[18:19]
	global_load_dwordx4 v[86:89], v232, s[18:19] offset:16
	global_load_dwordx4 v[90:93], v233, s[18:19]
	global_load_dwordx4 v[94:97], v233, s[18:19] offset:16
	global_load_dwordx4 v[98:101], v234, s[18:19]
	global_load_dwordx4 v[102:105], v234, s[18:19] offset:16
	global_load_dwordx4 v[106:109], v235, s[18:19]
	global_load_dwordx4 v[110:113], v235, s[18:19] offset:16
	global_load_dwordx4 v[114:117], v236, s[18:19]
	global_load_dwordx4 v[118:121], v236, s[18:19] offset:16
	global_load_dwordx4 v[122:125], v237, s[18:19]
	global_load_dwordx4 v[126:129], v237, s[18:19] offset:16
	s_add_i32 s22, s36, 3
	s_mul_i32 s22, s22, 0xb000
	s_add_i32 s23, s22, 0xffffa800
	s_add_i32 s24, s22, 0xffffd400
	s_add_i32 s25, s22, 0x2c00
	s_add_i32 s26, s36, 2
	s_mul_i32 s26, s26, 0x5800
	s_add_i32 s26, s26, 0x100b000
	s_add_i32 s27, s26, 0x2c00
	v_add_u32_e32 v232, s23, v1
	v_add_u32_e32 v233, s24, v1
	v_add_u32_e32 v234, s22, v1
	v_add_u32_e32 v235, s25, v1
	v_add_u32_e32 v236, s26, v1
	v_add_u32_e32 v237, s27, v1
	global_load_dwordx4 v[130:133], v232, s[18:19]
	global_load_dwordx4 v[134:137], v232, s[18:19] offset:16
	global_load_dwordx4 v[138:141], v233, s[18:19]
	global_load_dwordx4 v[142:145], v233, s[18:19] offset:16
	global_load_dwordx4 v[146:149], v234, s[18:19]
	global_load_dwordx4 v[150:153], v234, s[18:19] offset:16
	global_load_dwordx4 v[154:157], v235, s[18:19]
	global_load_dwordx4 v[158:161], v235, s[18:19] offset:16
	global_load_dwordx4 v[162:165], v236, s[18:19]
	global_load_dwordx4 v[166:169], v236, s[18:19] offset:16
	global_load_dwordx4 v[170:173], v237, s[18:19]
	global_load_dwordx4 v[174:177], v237, s[18:19] offset:16
	s_add_i32 s22, s36, 4
	s_mul_i32 s22, s22, 0xb000
	s_add_i32 s23, s22, 0xffffa800
	s_add_i32 s24, s22, 0xffffd400
	s_add_i32 s25, s22, 0x2c00
	s_add_i32 s26, s36, 3
	s_mul_i32 s26, s26, 0x5800
	s_add_i32 s26, s26, 0x100b000
	s_add_i32 s27, s26, 0x2c00
	v_add_u32_e32 v232, s23, v1
	v_add_u32_e32 v233, s24, v1
	v_add_u32_e32 v234, s22, v1
	v_add_u32_e32 v235, s25, v1
	v_add_u32_e32 v236, s26, v1
	v_add_u32_e32 v237, s27, v1
	global_load_dwordx4 v[184:187], v232, s[18:19]
	global_load_dwordx4 v[188:191], v232, s[18:19] offset:16
	global_load_dwordx4 v[192:195], v233, s[18:19]
	global_load_dwordx4 v[196:199], v233, s[18:19] offset:16
	global_load_dwordx4 v[200:203], v234, s[18:19]
	global_load_dwordx4 v[204:207], v234, s[18:19] offset:16
	global_load_dwordx4 v[208:211], v235, s[18:19]
	global_load_dwordx4 v[212:215], v235, s[18:19] offset:16
	global_load_dwordx4 v[216:219], v236, s[18:19]
	global_load_dwordx4 v[220:223], v236, s[18:19] offset:16
	global_load_dwordx4 v[224:227], v237, s[18:19]
	global_load_dwordx4 v[228:231], v237, s[18:19] offset:16
	v_mov_b32_e32 v180, 0xbfb8aa3b
	v_mov_b32_e32 v181, 0xbfb8aa3b
	v_lshlrev_b32_e32 v183, 4, v242
	s_waitcnt vmcnt(36)
	s_and_b32 s22, s36, 31
	s_cmp_lg_u32 s22, 0
	s_cbranch_scc1 .Lfx_notfirst
	v_mov_b32_e32 v34, 0
	v_mov_b32_e32 v35, 0
	v_mov_b32_e32 v36, 0
	v_mov_b32_e32 v37, 0
	v_mov_b32_e32 v38, 0
	v_mov_b32_e32 v39, 0
	v_mov_b32_e32 v40, 0
	v_mov_b32_e32 v41, 0
	v_mov_b32_e32 v42, 0
	v_mov_b32_e32 v43, 0
	v_mov_b32_e32 v44, 0
	v_mov_b32_e32 v45, 0
	v_mov_b32_e32 v46, 0
	v_mov_b32_e32 v47, 0
	v_mov_b32_e32 v48, 0
	v_mov_b32_e32 v49, 0
; #define GAS __attribute__((address_space(1)))
; __device__ __forceinline__ unsigned cvt_pk_bf16(float lo, float hi) { unsigned r; asm volatile("v_cvt_pk_bf16_f32 %0, %1, %2" : "=v"(r) : "v"(lo), "v"(hi)); return r; }
; __device__ __forceinline__ float fast_sigmoid(float g) { return __builtin_amdgcn_rcpf(1.f + __builtin_amdgcn_exp2f(-g * LOG2E)); }
; __device__ __forceinline__ void ffn_fixup(GAS bf16_t* __restrict__ act, const GAS float* __restrict__ SG, const GAS float* __restrict__ SU, const GAS float* __restrict__ cw, const GAS float* __restrict__ cb, int pm) {
;     ...
;         if (rr == 0) {
;             if (!first) { const f32x4 a = *(const GAS f32x4*)pv, b = *(const GAS f32x4*)(pv + 4), c = *(const GAS f32x4*)(pv + FFN), d = *(const GAS f32x4*)(pv + FFN + 4);
; #pragma unroll
;                 for (int e = 0; e < 4; ++e) { gm2[e] = a[e]; gm2[4 + e] = b[e]; gm1[e] = c[e]; gm1[4 + e] = d[e]; } }
;             const f32x4 a = *(const GAS f32x4*)c0, b = *(const GAS f32x4*)(c0 + 4);
; #pragma unroll
;             for (int e = 0; e < 4; ++e) { gc[e] = a[e]; gc[4 + e] = b[e]; }
;         } else {
;             if (!first) { const f32x4 c = *(const GAS f32x4*)(pv + FFN), d = *(const GAS f32x4*)(pv + FFN + 4);
; #pragma unroll
;                 for (int e = 0; e < 4; ++e) { gm2[e] = c[e]; gm2[4 + e] = d[e]; } }
;             const f32x4 a = *(const GAS f32x4*)c0, b = *(const GAS f32x4*)(c0 + 4), c = *(const GAS f32x4*)(c0 + FFN), d = *(const GAS f32x4*)(c0 + FFN + 4);
; #pragma unroll
;             for (int e = 0; e < 4; ++e) { gm1[e] = a[e]; gm1[4 + e] = b[e]; gc[e] = c[e]; gc[4 + e] = d[e]; }
;         }
;     ...
;         float o[8];
; #pragma unroll
;         for (int e = 0; e < 8; ++e) { const float cv = cb[f0 + e] + cw[f0 + e] * gm2[e] + cw[FFN + f0 + e] * gm1[e] + cw[2 * FFN + f0 + e] * gc[e]; o[e] = cv * fast_sigmoid(cv) * up[e]; }
;         u32x4 w; w.x = cvt_pk_bf16(o[0], o[1]); w.y = cvt_pk_bf16(o[2], o[3]); w.z = cvt_pk_bf16(o[4], o[5]); w.w = cvt_pk_bf16(o[6], o[7]);
;         *(GAS u32x4*)(act + (size_t)row * FFN + f0) = w;
;     }
.Lfx_notfirst:
	v_pk_fma_f32 v[34:35], v[34:35], v[2:3], v[26:27]
	v_pk_fma_f32 v[36:37], v[36:37], v[4:5], v[28:29]
	v_pk_fma_f32 v[38:39], v[38:39], v[6:7], v[30:31]
	v_pk_fma_f32 v[40:41], v[40:41], v[8:9], v[32:33]
	v_pk_mul_f32 v[232:233], v[42:43], v[10:11]
	v_pk_mul_f32 v[234:235], v[44:45], v[12:13]
	v_pk_mul_f32 v[236:237], v[46:47], v[14:15]
	v_pk_mul_f32 v[238:239], v[48:49], v[16:17]
	v_pk_add_f32 v[34:35], v[34:35], v[232:233]
	v_pk_add_f32 v[36:37], v[36:37], v[234:235]
	v_pk_add_f32 v[38:39], v[38:39], v[236:237]
	v_pk_add_f32 v[40:41], v[40:41], v[238:239]
	v_pk_mul_f32 v[232:233], v[50:51], v[18:19]
	v_pk_mul_f32 v[234:235], v[52:53], v[20:21]
	v_pk_mul_f32 v[236:237], v[54:55], v[22:23]
	v_pk_mul_f32 v[238:239], v[56:57], v[24:25]
	v_pk_add_f32 v[34:35], v[34:35], v[232:233]
	v_pk_add_f32 v[36:37], v[36:37], v[234:235]
	v_pk_add_f32 v[38:39], v[38:39], v[236:237]
	v_pk_add_f32 v[40:41], v[40:41], v[238:239]
	v_pk_mul_f32 v[232:233], v[34:35], v[180:181]
	v_pk_mul_f32 v[234:235], v[36:37], v[180:181]
	v_pk_mul_f32 v[236:237], v[38:39], v[180:181]
	v_pk_mul_f32 v[238:239], v[40:41], v[180:181]
	v_exp_f32_e32 v232, v232
	v_exp_f32_e32 v233, v233
	v_exp_f32_e32 v234, v234
	v_exp_f32_e32 v235, v235
	v_exp_f32_e32 v236, v236
	v_exp_f32_e32 v237, v237
	v_exp_f32_e32 v238, v238
	v_exp_f32_e32 v239, v239
	v_add_f32_e32 v232, 1.0, v232
	v_add_f32_e32 v233, 1.0, v233
	v_add_f32_e32 v234, 1.0, v234
	v_add_f32_e32 v235, 1.0, v235
	v_add_f32_e32 v236, 1.0, v236
	v_add_f32_e32 v237, 1.0, v237
	v_add_f32_e32 v238, 1.0, v238
	v_add_f32_e32 v239, 1.0, v239
	v_rcp_f32_e32 v232, v232
	v_rcp_f32_e32 v233, v233
	v_rcp_f32_e32 v234, v234
	v_rcp_f32_e32 v235, v235
	v_rcp_f32_e32 v236, v236
	v_rcp_f32_e32 v237, v237
	v_rcp_f32_e32 v238, v238
	v_rcp_f32_e32 v239, v239
	v_pk_mul_f32 v[34:35], v[34:35], v[232:233]
	v_pk_mul_f32 v[36:37], v[36:37], v[234:235]
	v_pk_mul_f32 v[38:39], v[38:39], v[236:237]
	v_pk_mul_f32 v[40:41], v[40:41], v[238:239]
	v_pk_mul_f32 v[34:35], v[66:67], v[34:35]
	v_pk_mul_f32 v[36:37], v[68:69], v[36:37]
	v_pk_mul_f32 v[38:39], v[70:71], v[38:39]
	v_pk_mul_f32 v[40:41], v[72:73], v[40:41]
	v_cvt_pk_bf16_f32 v34, v34, v35
	v_cvt_pk_bf16_f32 v35, v36, v37
	v_cvt_pk_bf16_f32 v36, v38, v39
	v_cvt_pk_bf16_f32 v37, v40, v41
	s_add_i32 s22, s36, 0
	s_mul_i32 s22, s22, 0x58000
	v_add_u32_e32 v232, s22, v183
	global_store_dwordx4 v232, v[34:37], s[20:21]
	s_nop 1
	v_pk_fma_f32 v[42:43], v[42:43], v[2:3], v[26:27]
	v_pk_fma_f32 v[44:45], v[44:45], v[4:5], v[28:29]
	v_pk_fma_f32 v[46:47], v[46:47], v[6:7], v[30:31]
	v_pk_fma_f32 v[48:49], v[48:49], v[8:9], v[32:33]
	v_pk_mul_f32 v[232:233], v[50:51], v[10:11]
	v_pk_mul_f32 v[234:235], v[52:53], v[12:13]
	v_pk_mul_f32 v[236:237], v[54:55], v[14:15]
	v_pk_mul_f32 v[238:239], v[56:57], v[16:17]
	v_pk_add_f32 v[42:43], v[42:43], v[232:233]
	v_pk_add_f32 v[44:45], v[44:45], v[234:235]
	v_pk_add_f32 v[46:47], v[46:47], v[236:237]
	v_pk_add_f32 v[48:49], v[48:49], v[238:239]
	v_pk_mul_f32 v[232:233], v[58:59], v[18:19]
	v_pk_mul_f32 v[234:235], v[60:61], v[20:21]
	v_pk_mul_f32 v[236:237], v[62:63], v[22:23]
	v_pk_mul_f32 v[238:239], v[64:65], v[24:25]
	v_pk_add_f32 v[42:43], v[42:43], v[232:233]
	v_pk_add_f32 v[44:45], v[44:45], v[234:235]
	v_pk_add_f32 v[46:47], v[46:47], v[236:237]
	v_pk_add_f32 v[48:49], v[48:49], v[238:239]
	v_pk_mul_f32 v[232:233], v[42:43], v[180:181]
	v_pk_mul_f32 v[234:235], v[44:45], v[180:181]
	v_pk_mul_f32 v[236:237], v[46:47], v[180:181]
	v_pk_mul_f32 v[238:239], v[48:49], v[180:181]
	v_exp_f32_e32 v232, v232
	v_exp_f32_e32 v233, v233
	v_exp_f32_e32 v234, v234
	v_exp_f32_e32 v235, v235
	v_exp_f32_e32 v236, v236
	v_exp_f32_e32 v237, v237
	v_exp_f32_e32 v238, v238
	v_exp_f32_e32 v239, v239
	v_add_f32_e32 v232, 1.0, v232
	v_add_f32_e32 v233, 1.0, v233
	v_add_f32_e32 v234, 1.0, v234
	v_add_f32_e32 v235, 1.0, v235
	v_add_f32_e32 v236, 1.0, v236
	v_add_f32_e32 v237, 1.0, v237
	v_add_f32_e32 v238, 1.0, v238
	v_add_f32_e32 v239, 1.0, v239
	v_rcp_f32_e32 v232, v232
	v_rcp_f32_e32 v233, v233
	v_rcp_f32_e32 v234, v234
	v_rcp_f32_e32 v235, v235
	v_rcp_f32_e32 v236, v236
	v_rcp_f32_e32 v237, v237
	v_rcp_f32_e32 v238, v238
	v_rcp_f32_e32 v239, v239
	v_pk_mul_f32 v[42:43], v[42:43], v[232:233]
	v_pk_mul_f32 v[44:45], v[44:45], v[234:235]
	v_pk_mul_f32 v[46:47], v[46:47], v[236:237]
	v_pk_mul_f32 v[48:49], v[48:49], v[238:239]
	v_pk_mul_f32 v[42:43], v[74:75], v[42:43]
	v_pk_mul_f32 v[44:45], v[76:77], v[44:45]
	v_pk_mul_f32 v[46:47], v[78:79], v[46:47]
	v_pk_mul_f32 v[48:49], v[80:81], v[48:49]
	v_cvt_pk_bf16_f32 v42, v42, v43
	v_cvt_pk_bf16_f32 v43, v44, v45
	v_cvt_pk_bf16_f32 v44, v46, v47
	v_cvt_pk_bf16_f32 v45, v48, v49
	s_add_i32 s22, s36, 0
	s_mul_i32 s22, s22, 0x58000
	s_add_i32 s22, s22, 0x1600
	v_add_u32_e32 v232, s22, v183
	global_store_dwordx4 v232, v[42:45], s[20:21]
	s_nop 1
	s_waitcnt vmcnt(24)
; #define GAS __attribute__((address_space(1)))
; __device__ __forceinline__ unsigned cvt_pk_bf16(float lo, float hi) { unsigned r; asm volatile("v_cvt_pk_bf16_f32 %0, %1, %2" : "=v"(r) : "v"(lo), "v"(hi)); return r; }
; __device__ __forceinline__ float fast_sigmoid(float g) { return __builtin_amdgcn_rcpf(1.f + __builtin_amdgcn_exp2f(-g * LOG2E)); }
; __device__ __forceinline__ void ffn_fixup(GAS bf16_t* __restrict__ act, const GAS float* __restrict__ SG, const GAS float* __restrict__ SU, const GAS float* __restrict__ cw, const GAS float* __restrict__ cb, int pm) {
;     ...
;         float o[8];
; #pragma unroll
;         for (int e = 0; e < 8; ++e) { const float cv = cb[f0 + e] + cw[f0 + e] * gm2[e] + cw[FFN + f0 + e] * gm1[e] + cw[2 * FFN + f0 + e] * gc[e]; o[e] = cv * fast_sigmoid(cv) * up[e]; }
;         u32x4 w; w.x = cvt_pk_bf16(o[0], o[1]); w.y = cvt_pk_bf16(o[2], o[3]); w.z = cvt_pk_bf16(o[4], o[5]); w.w = cvt_pk_bf16(o[6], o[7]);
;         *(GAS u32x4*)(act + (size_t)row * FFN + f0) = w;
;     }
	v_pk_fma_f32 v[82:83], v[82:83], v[2:3], v[26:27]
	v_pk_fma_f32 v[84:85], v[84:85], v[4:5], v[28:29]
	v_pk_fma_f32 v[86:87], v[86:87], v[6:7], v[30:31]
	v_pk_fma_f32 v[88:89], v[88:89], v[8:9], v[32:33]
	v_pk_mul_f32 v[232:233], v[90:91], v[10:11]
	v_pk_mul_f32 v[234:235], v[92:93], v[12:13]
	v_pk_mul_f32 v[236:237], v[94:95], v[14:15]
	v_pk_mul_f32 v[238:239], v[96:97], v[16:17]
	v_pk_add_f32 v[82:83], v[82:83], v[232:233]
	v_pk_add_f32 v[84:85], v[84:85], v[234:235]
	v_pk_add_f32 v[86:87], v[86:87], v[236:237]
	v_pk_add_f32 v[88:89], v[88:89], v[238:239]
	v_pk_mul_f32 v[232:233], v[98:99], v[18:19]
	v_pk_mul_f32 v[234:235], v[100:101], v[20:21]
	v_pk_mul_f32 v[236:237], v[102:103], v[22:23]
	v_pk_mul_f32 v[238:239], v[104:105], v[24:25]
	v_pk_add_f32 v[82:83], v[82:83], v[232:233]
	v_pk_add_f32 v[84:85], v[84:85], v[234:235]
	v_pk_add_f32 v[86:87], v[86:87], v[236:237]
	v_pk_add_f32 v[88:89], v[88:89], v[238:239]
	v_pk_mul_f32 v[232:233], v[82:83], v[180:181]
	v_pk_mul_f32 v[234:235], v[84:85], v[180:181]
	v_pk_mul_f32 v[236:237], v[86:87], v[180:181]
	v_pk_mul_f32 v[238:239], v[88:89], v[180:181]
	v_exp_f32_e32 v232, v232
	v_exp_f32_e32 v233, v233
	v_exp_f32_e32 v234, v234
	v_exp_f32_e32 v235, v235
	v_exp_f32_e32 v236, v236
	v_exp_f32_e32 v237, v237
	v_exp_f32_e32 v238, v238
	v_exp_f32_e32 v239, v239
	v_add_f32_e32 v232, 1.0, v232
	v_add_f32_e32 v233, 1.0, v233
	v_add_f32_e32 v234, 1.0, v234
	v_add_f32_e32 v235, 1.0, v235
	v_add_f32_e32 v236, 1.0, v236
	v_add_f32_e32 v237, 1.0, v237
	v_add_f32_e32 v238, 1.0, v238
	v_add_f32_e32 v239, 1.0, v239
	v_rcp_f32_e32 v232, v232
	v_rcp_f32_e32 v233, v233
	v_rcp_f32_e32 v234, v234
	v_rcp_f32_e32 v235, v235
	v_rcp_f32_e32 v236, v236
	v_rcp_f32_e32 v237, v237
	v_rcp_f32_e32 v238, v238
	v_rcp_f32_e32 v239, v239
	v_pk_mul_f32 v[82:83], v[82:83], v[232:233]
	v_pk_mul_f32 v[84:85], v[84:85], v[234:235]
	v_pk_mul_f32 v[86:87], v[86:87], v[236:237]
	v_pk_mul_f32 v[88:89], v[88:89], v[238:239]
	v_pk_mul_f32 v[82:83], v[114:115], v[82:83]
	v_pk_mul_f32 v[84:85], v[116:117], v[84:85]
	v_pk_mul_f32 v[86:87], v[118:119], v[86:87]
	v_pk_mul_f32 v[88:89], v[120:121], v[88:89]
	v_cvt_pk_bf16_f32 v82, v82, v83
	v_cvt_pk_bf16_f32 v83, v84, v85
	v_cvt_pk_bf16_f32 v84, v86, v87
	v_cvt_pk_bf16_f32 v85, v88, v89
	s_add_i32 s22, s36, 1
	s_mul_i32 s22, s22, 0x58000
	v_add_u32_e32 v232, s22, v183
	global_store_dwordx4 v232, v[82:85], s[20:21]
	s_nop 1
	v_pk_fma_f32 v[90:91], v[90:91], v[2:3], v[26:27]
	v_pk_fma_f32 v[92:93], v[92:93], v[4:5], v[28:29]
	v_pk_fma_f32 v[94:95], v[94:95], v[6:7], v[30:31]
	v_pk_fma_f32 v[96:97], v[96:97], v[8:9], v[32:33]
	v_pk_mul_f32 v[232:233], v[98:99], v[10:11]
	v_pk_mul_f32 v[234:235], v[100:101], v[12:13]
	v_pk_mul_f32 v[236:237], v[102:103], v[14:15]
	v_pk_mul_f32 v[238:239], v[104:105], v[16:17]
	v_pk_add_f32 v[90:91], v[90:91], v[232:233]
	v_pk_add_f32 v[92:93], v[92:93], v[234:235]
	v_pk_add_f32 v[94:95], v[94:95], v[236:237]
	v_pk_add_f32 v[96:97], v[96:97], v[238:239]
	v_pk_mul_f32 v[232:233], v[106:107], v[18:19]
	v_pk_mul_f32 v[234:235], v[108:109], v[20:21]
	v_pk_mul_f32 v[236:237], v[110:111], v[22:23]
	v_pk_mul_f32 v[238:239], v[112:113], v[24:25]
	v_pk_add_f32 v[90:91], v[90:91], v[232:233]
	v_pk_add_f32 v[92:93], v[92:93], v[234:235]
	v_pk_add_f32 v[94:95], v[94:95], v[236:237]
	v_pk_add_f32 v[96:97], v[96:97], v[238:239]
	v_pk_mul_f32 v[232:233], v[90:91], v[180:181]
	v_pk_mul_f32 v[234:235], v[92:93], v[180:181]
	v_pk_mul_f32 v[236:237], v[94:95], v[180:181]
	v_pk_mul_f32 v[238:239], v[96:97], v[180:181]
	v_exp_f32_e32 v232, v232
	v_exp_f32_e32 v233, v233
	v_exp_f32_e32 v234, v234
	v_exp_f32_e32 v235, v235
	v_exp_f32_e32 v236, v236
	v_exp_f32_e32 v237, v237
	v_exp_f32_e32 v238, v238
	v_exp_f32_e32 v239, v239
	v_add_f32_e32 v232, 1.0, v232
	v_add_f32_e32 v233, 1.0, v233
	v_add_f32_e32 v234, 1.0, v234
	v_add_f32_e32 v235, 1.0, v235
	v_add_f32_e32 v236, 1.0, v236
	v_add_f32_e32 v237, 1.0, v237
	v_add_f32_e32 v238, 1.0, v238
	v_add_f32_e32 v239, 1.0, v239
	v_rcp_f32_e32 v232, v232
	v_rcp_f32_e32 v233, v233
	v_rcp_f32_e32 v234, v234
	v_rcp_f32_e32 v235, v235
	v_rcp_f32_e32 v236, v236
	v_rcp_f32_e32 v237, v237
	v_rcp_f32_e32 v238, v238
	v_rcp_f32_e32 v239, v239
	v_pk_mul_f32 v[90:91], v[90:91], v[232:233]
	v_pk_mul_f32 v[92:93], v[92:93], v[234:235]
	v_pk_mul_f32 v[94:95], v[94:95], v[236:237]
	v_pk_mul_f32 v[96:97], v[96:97], v[238:239]
	v_pk_mul_f32 v[90:91], v[122:123], v[90:91]
	v_pk_mul_f32 v[92:93], v[124:125], v[92:93]
	v_pk_mul_f32 v[94:95], v[126:127], v[94:95]
	v_pk_mul_f32 v[96:97], v[128:129], v[96:97]
	v_cvt_pk_bf16_f32 v90, v90, v91
	v_cvt_pk_bf16_f32 v91, v92, v93
	v_cvt_pk_bf16_f32 v92, v94, v95
	v_cvt_pk_bf16_f32 v93, v96, v97
	s_add_i32 s22, s36, 1
	s_mul_i32 s22, s22, 0x58000
	s_add_i32 s22, s22, 0x1600
	v_add_u32_e32 v232, s22, v183
	global_store_dwordx4 v232, v[90:93], s[20:21]
	s_nop 1
	s_waitcnt vmcnt(12)
; #define GAS __attribute__((address_space(1)))
; __device__ __forceinline__ unsigned cvt_pk_bf16(float lo, float hi) { unsigned r; asm volatile("v_cvt_pk_bf16_f32 %0, %1, %2" : "=v"(r) : "v"(lo), "v"(hi)); return r; }
; __device__ __forceinline__ float fast_sigmoid(float g) { return __builtin_amdgcn_rcpf(1.f + __builtin_amdgcn_exp2f(-g * LOG2E)); }
; __device__ __forceinline__ void ffn_fixup(GAS bf16_t* __restrict__ act, const GAS float* __restrict__ SG, const GAS float* __restrict__ SU, const GAS float* __restrict__ cw, const GAS float* __restrict__ cb, int pm) {
;     ...
;         float o[8];
; #pragma unroll
;         for (int e = 0; e < 8; ++e) { const float cv = cb[f0 + e] + cw[f0 + e] * gm2[e] + cw[FFN + f0 + e] * gm1[e] + cw[2 * FFN + f0 + e] * gc[e]; o[e] = cv * fast_sigmoid(cv) * up[e]; }
;         u32x4 w; w.x = cvt_pk_bf16(o[0], o[1]); w.y = cvt_pk_bf16(o[2], o[3]); w.z = cvt_pk_bf16(o[4], o[5]); w.w = cvt_pk_bf16(o[6], o[7]);
;         *(GAS u32x4*)(act + (size_t)row * FFN + f0) = w;
;     }
	v_pk_fma_f32 v[130:131], v[130:131], v[2:3], v[26:27]
	v_pk_fma_f32 v[132:133], v[132:133], v[4:5], v[28:29]
	v_pk_fma_f32 v[134:135], v[134:135], v[6:7], v[30:31]
	v_pk_fma_f32 v[136:137], v[136:137], v[8:9], v[32:33]
	v_pk_mul_f32 v[232:233], v[138:139], v[10:11]
	v_pk_mul_f32 v[234:235], v[140:141], v[12:13]
	v_pk_mul_f32 v[236:237], v[142:143], v[14:15]
	v_pk_mul_f32 v[238:239], v[144:145], v[16:17]
	v_pk_add_f32 v[130:131], v[130:131], v[232:233]
	v_pk_add_f32 v[132:133], v[132:133], v[234:235]
	v_pk_add_f32 v[134:135], v[134:135], v[236:237]
	v_pk_add_f32 v[136:137], v[136:137], v[238:239]
	v_pk_mul_f32 v[232:233], v[146:147], v[18:19]
	v_pk_mul_f32 v[234:235], v[148:149], v[20:21]
	v_pk_mul_f32 v[236:237], v[150:151], v[22:23]
	v_pk_mul_f32 v[238:239], v[152:153], v[24:25]
	v_pk_add_f32 v[130:131], v[130:131], v[232:233]
	v_pk_add_f32 v[132:133], v[132:133], v[234:235]
	v_pk_add_f32 v[134:135], v[134:135], v[236:237]
	v_pk_add_f32 v[136:137], v[136:137], v[238:239]
	v_pk_mul_f32 v[232:233], v[130:131], v[180:181]
	v_pk_mul_f32 v[234:235], v[132:133], v[180:181]
	v_pk_mul_f32 v[236:237], v[134:135], v[180:181]
	v_pk_mul_f32 v[238:239], v[136:137], v[180:181]
	v_exp_f32_e32 v232, v232
	v_exp_f32_e32 v233, v233
	v_exp_f32_e32 v234, v234
	v_exp_f32_e32 v235, v235
	v_exp_f32_e32 v236, v236
	v_exp_f32_e32 v237, v237
	v_exp_f32_e32 v238, v238
	v_exp_f32_e32 v239, v239
	v_add_f32_e32 v232, 1.0, v232
	v_add_f32_e32 v233, 1.0, v233
	v_add_f32_e32 v234, 1.0, v234
	v_add_f32_e32 v235, 1.0, v235
	v_add_f32_e32 v236, 1.0, v236
	v_add_f32_e32 v237, 1.0, v237
	v_add_f32_e32 v238, 1.0, v238
	v_add_f32_e32 v239, 1.0, v239
	v_rcp_f32_e32 v232, v232
	v_rcp_f32_e32 v233, v233
	v_rcp_f32_e32 v234, v234
	v_rcp_f32_e32 v235, v235
	v_rcp_f32_e32 v236, v236
	v_rcp_f32_e32 v237, v237
	v_rcp_f32_e32 v238, v238
	v_rcp_f32_e32 v239, v239
	v_pk_mul_f32 v[130:131], v[130:131], v[232:233]
	v_pk_mul_f32 v[132:133], v[132:133], v[234:235]
	v_pk_mul_f32 v[134:135], v[134:135], v[236:237]
	v_pk_mul_f32 v[136:137], v[136:137], v[238:239]
	v_pk_mul_f32 v[130:131], v[162:163], v[130:131]
	v_pk_mul_f32 v[132:133], v[164:165], v[132:133]
	v_pk_mul_f32 v[134:135], v[166:167], v[134:135]
	v_pk_mul_f32 v[136:137], v[168:169], v[136:137]
	v_cvt_pk_bf16_f32 v130, v130, v131
	v_cvt_pk_bf16_f32 v131, v132, v133
	v_cvt_pk_bf16_f32 v132, v134, v135
	v_cvt_pk_bf16_f32 v133, v136, v137
	s_add_i32 s22, s36, 2
	s_mul_i32 s22, s22, 0x58000
	v_add_u32_e32 v232, s22, v183
	global_store_dwordx4 v232, v[130:133], s[20:21]
	s_nop 1
	v_pk_fma_f32 v[138:139], v[138:139], v[2:3], v[26:27]
	v_pk_fma_f32 v[140:141], v[140:141], v[4:5], v[28:29]
	v_pk_fma_f32 v[142:143], v[142:143], v[6:7], v[30:31]
	v_pk_fma_f32 v[144:145], v[144:145], v[8:9], v[32:33]
	v_pk_mul_f32 v[232:233], v[146:147], v[10:11]
	v_pk_mul_f32 v[234:235], v[148:149], v[12:13]
	v_pk_mul_f32 v[236:237], v[150:151], v[14:15]
	v_pk_mul_f32 v[238:239], v[152:153], v[16:17]
	v_pk_add_f32 v[138:139], v[138:139], v[232:233]
	v_pk_add_f32 v[140:141], v[140:141], v[234:235]
	v_pk_add_f32 v[142:143], v[142:143], v[236:237]
	v_pk_add_f32 v[144:145], v[144:145], v[238:239]
	v_pk_mul_f32 v[232:233], v[154:155], v[18:19]
	v_pk_mul_f32 v[234:235], v[156:157], v[20:21]
	v_pk_mul_f32 v[236:237], v[158:159], v[22:23]
	v_pk_mul_f32 v[238:239], v[160:161], v[24:25]
	v_pk_add_f32 v[138:139], v[138:139], v[232:233]
	v_pk_add_f32 v[140:141], v[140:141], v[234:235]
	v_pk_add_f32 v[142:143], v[142:143], v[236:237]
	v_pk_add_f32 v[144:145], v[144:145], v[238:239]
	v_pk_mul_f32 v[232:233], v[138:139], v[180:181]
	v_pk_mul_f32 v[234:235], v[140:141], v[180:181]
	v_pk_mul_f32 v[236:237], v[142:143], v[180:181]
	v_pk_mul_f32 v[238:239], v[144:145], v[180:181]
	v_exp_f32_e32 v232, v232
	v_exp_f32_e32 v233, v233
	v_exp_f32_e32 v234, v234
	v_exp_f32_e32 v235, v235
	v_exp_f32_e32 v236, v236
	v_exp_f32_e32 v237, v237
	v_exp_f32_e32 v238, v238
	v_exp_f32_e32 v239, v239
	v_add_f32_e32 v232, 1.0, v232
	v_add_f32_e32 v233, 1.0, v233
	v_add_f32_e32 v234, 1.0, v234
	v_add_f32_e32 v235, 1.0, v235
	v_add_f32_e32 v236, 1.0, v236
	v_add_f32_e32 v237, 1.0, v237
	v_add_f32_e32 v238, 1.0, v238
	v_add_f32_e32 v239, 1.0, v239
	v_rcp_f32_e32 v232, v232
	v_rcp_f32_e32 v233, v233
	v_rcp_f32_e32 v234, v234
	v_rcp_f32_e32 v235, v235
	v_rcp_f32_e32 v236, v236
	v_rcp_f32_e32 v237, v237
	v_rcp_f32_e32 v238, v238
	v_rcp_f32_e32 v239, v239
	v_pk_mul_f32 v[138:139], v[138:139], v[232:233]
	v_pk_mul_f32 v[140:141], v[140:141], v[234:235]
	v_pk_mul_f32 v[142:143], v[142:143], v[236:237]
	v_pk_mul_f32 v[144:145], v[144:145], v[238:239]
	v_pk_mul_f32 v[138:139], v[170:171], v[138:139]
	v_pk_mul_f32 v[140:141], v[172:173], v[140:141]
	v_pk_mul_f32 v[142:143], v[174:175], v[142:143]
	v_pk_mul_f32 v[144:145], v[176:177], v[144:145]
	v_cvt_pk_bf16_f32 v138, v138, v139
	v_cvt_pk_bf16_f32 v139, v140, v141
	v_cvt_pk_bf16_f32 v140, v142, v143
	v_cvt_pk_bf16_f32 v141, v144, v145
	s_add_i32 s22, s36, 2
	s_mul_i32 s22, s22, 0x58000
	s_add_i32 s22, s22, 0x1600
	v_add_u32_e32 v232, s22, v183
	global_store_dwordx4 v232, v[138:141], s[20:21]
	s_nop 1
	s_waitcnt vmcnt(0)
; #define GAS __attribute__((address_space(1)))
; __device__ __forceinline__ unsigned cvt_pk_bf16(float lo, float hi) { unsigned r; asm volatile("v_cvt_pk_bf16_f32 %0, %1, %2" : "=v"(r) : "v"(lo), "v"(hi)); return r; }
; __device__ __forceinline__ float fast_sigmoid(float g) { return __builtin_amdgcn_rcpf(1.f + __builtin_amdgcn_exp2f(-g * LOG2E)); }
; __device__ __forceinline__ void ffn_fixup(GAS bf16_t* __restrict__ act, const GAS float* __restrict__ SG, const GAS float* __restrict__ SU, const GAS float* __restrict__ cw, const GAS float* __restrict__ cb, int pm) {
;     ...
;         float o[8];
; #pragma unroll
;         for (int e = 0; e < 8; ++e) { const float cv = cb[f0 + e] + cw[f0 + e] * gm2[e] + cw[FFN + f0 + e] * gm1[e] + cw[2 * FFN + f0 + e] * gc[e]; o[e] = cv * fast_sigmoid(cv) * up[e]; }
;         u32x4 w; w.x = cvt_pk_bf16(o[0], o[1]); w.y = cvt_pk_bf16(o[2], o[3]); w.z = cvt_pk_bf16(o[4], o[5]); w.w = cvt_pk_bf16(o[6], o[7]);
;         *(GAS u32x4*)(act + (size_t)row * FFN + f0) = w;
;     }
	v_pk_fma_f32 v[184:185], v[184:185], v[2:3], v[26:27]
	v_pk_fma_f32 v[186:187], v[186:187], v[4:5], v[28:29]
	v_pk_fma_f32 v[188:189], v[188:189], v[6:7], v[30:31]
	v_pk_fma_f32 v[190:191], v[190:191], v[8:9], v[32:33]
	v_pk_mul_f32 v[232:233], v[192:193], v[10:11]
	v_pk_mul_f32 v[234:235], v[194:195], v[12:13]
	v_pk_mul_f32 v[236:237], v[196:197], v[14:15]
	v_pk_mul_f32 v[238:239], v[198:199], v[16:17]
	v_pk_add_f32 v[184:185], v[184:185], v[232:233]
	v_pk_add_f32 v[186:187], v[186:187], v[234:235]
	v_pk_add_f32 v[188:189], v[188:189], v[236:237]
	v_pk_add_f32 v[190:191], v[190:191], v[238:239]
	v_pk_mul_f32 v[232:233], v[200:201], v[18:19]
	v_pk_mul_f32 v[234:235], v[202:203], v[20:21]
	v_pk_mul_f32 v[236:237], v[204:205], v[22:23]
	v_pk_mul_f32 v[238:239], v[206:207], v[24:25]
	v_pk_add_f32 v[184:185], v[184:185], v[232:233]
	v_pk_add_f32 v[186:187], v[186:187], v[234:235]
	v_pk_add_f32 v[188:189], v[188:189], v[236:237]
	v_pk_add_f32 v[190:191], v[190:191], v[238:239]
	v_pk_mul_f32 v[232:233], v[184:185], v[180:181]
	v_pk_mul_f32 v[234:235], v[186:187], v[180:181]
	v_pk_mul_f32 v[236:237], v[188:189], v[180:181]
	v_pk_mul_f32 v[238:239], v[190:191], v[180:181]
	v_exp_f32_e32 v232, v232
	v_exp_f32_e32 v233, v233
	v_exp_f32_e32 v234, v234
	v_exp_f32_e32 v235, v235
	v_exp_f32_e32 v236, v236
	v_exp_f32_e32 v237, v237
	v_exp_f32_e32 v238, v238
	v_exp_f32_e32 v239, v239
	v_add_f32_e32 v232, 1.0, v232
	v_add_f32_e32 v233, 1.0, v233
	v_add_f32_e32 v234, 1.0, v234
	v_add_f32_e32 v235, 1.0, v235
	v_add_f32_e32 v236, 1.0, v236
	v_add_f32_e32 v237, 1.0, v237
	v_add_f32_e32 v238, 1.0, v238
	v_add_f32_e32 v239, 1.0, v239
	v_rcp_f32_e32 v232, v232
	v_rcp_f32_e32 v233, v233
	v_rcp_f32_e32 v234, v234
	v_rcp_f32_e32 v235, v235
	v_rcp_f32_e32 v236, v236
	v_rcp_f32_e32 v237, v237
	v_rcp_f32_e32 v238, v238
	v_rcp_f32_e32 v239, v239
	v_pk_mul_f32 v[184:185], v[184:185], v[232:233]
	v_pk_mul_f32 v[186:187], v[186:187], v[234:235]
	v_pk_mul_f32 v[188:189], v[188:189], v[236:237]
	v_pk_mul_f32 v[190:191], v[190:191], v[238:239]
	v_pk_mul_f32 v[184:185], v[216:217], v[184:185]
	v_pk_mul_f32 v[186:187], v[218:219], v[186:187]
	v_pk_mul_f32 v[188:189], v[220:221], v[188:189]
	v_pk_mul_f32 v[190:191], v[222:223], v[190:191]
	v_cvt_pk_bf16_f32 v184, v184, v185
	v_cvt_pk_bf16_f32 v185, v186, v187
	v_cvt_pk_bf16_f32 v186, v188, v189
	v_cvt_pk_bf16_f32 v187, v190, v191
	s_add_i32 s22, s36, 3
	s_mul_i32 s22, s22, 0x58000
	v_add_u32_e32 v232, s22, v183
	global_store_dwordx4 v232, v[184:187], s[20:21]
	s_nop 1
	v_pk_fma_f32 v[192:193], v[192:193], v[2:3], v[26:27]
	v_pk_fma_f32 v[194:195], v[194:195], v[4:5], v[28:29]
	v_pk_fma_f32 v[196:197], v[196:197], v[6:7], v[30:31]
	v_pk_fma_f32 v[198:199], v[198:199], v[8:9], v[32:33]
	v_pk_mul_f32 v[232:233], v[200:201], v[10:11]
	v_pk_mul_f32 v[234:235], v[202:203], v[12:13]
	v_pk_mul_f32 v[236:237], v[204:205], v[14:15]
	v_pk_mul_f32 v[238:239], v[206:207], v[16:17]
	v_pk_add_f32 v[192:193], v[192:193], v[232:233]
	v_pk_add_f32 v[194:195], v[194:195], v[234:235]
	v_pk_add_f32 v[196:197], v[196:197], v[236:237]
	v_pk_add_f32 v[198:199], v[198:199], v[238:239]
	v_pk_mul_f32 v[232:233], v[208:209], v[18:19]
	v_pk_mul_f32 v[234:235], v[210:211], v[20:21]
	v_pk_mul_f32 v[236:237], v[212:213], v[22:23]
	v_pk_mul_f32 v[238:239], v[214:215], v[24:25]
	v_pk_add_f32 v[192:193], v[192:193], v[232:233]
	v_pk_add_f32 v[194:195], v[194:195], v[234:235]
	v_pk_add_f32 v[196:197], v[196:197], v[236:237]
	v_pk_add_f32 v[198:199], v[198:199], v[238:239]
	v_pk_mul_f32 v[232:233], v[192:193], v[180:181]
	v_pk_mul_f32 v[234:235], v[194:195], v[180:181]
	v_pk_mul_f32 v[236:237], v[196:197], v[180:181]
	v_pk_mul_f32 v[238:239], v[198:199], v[180:181]
	v_exp_f32_e32 v232, v232
	v_exp_f32_e32 v233, v233
	v_exp_f32_e32 v234, v234
	v_exp_f32_e32 v235, v235
	v_exp_f32_e32 v236, v236
	v_exp_f32_e32 v237, v237
	v_exp_f32_e32 v238, v238
	v_exp_f32_e32 v239, v239
	v_add_f32_e32 v232, 1.0, v232
	v_add_f32_e32 v233, 1.0, v233
	v_add_f32_e32 v234, 1.0, v234
	v_add_f32_e32 v235, 1.0, v235
	v_add_f32_e32 v236, 1.0, v236
	v_add_f32_e32 v237, 1.0, v237
	v_add_f32_e32 v238, 1.0, v238
	v_add_f32_e32 v239, 1.0, v239
	v_rcp_f32_e32 v232, v232
	v_rcp_f32_e32 v233, v233
	v_rcp_f32_e32 v234, v234
	v_rcp_f32_e32 v235, v235
	v_rcp_f32_e32 v236, v236
	v_rcp_f32_e32 v237, v237
	v_rcp_f32_e32 v238, v238
	v_rcp_f32_e32 v239, v239
	v_pk_mul_f32 v[192:193], v[192:193], v[232:233]
	v_pk_mul_f32 v[194:195], v[194:195], v[234:235]
	v_pk_mul_f32 v[196:197], v[196:197], v[236:237]
	v_pk_mul_f32 v[198:199], v[198:199], v[238:239]
	v_pk_mul_f32 v[192:193], v[224:225], v[192:193]
	v_pk_mul_f32 v[194:195], v[226:227], v[194:195]
	v_pk_mul_f32 v[196:197], v[228:229], v[196:197]
	v_pk_mul_f32 v[198:199], v[230:231], v[198:199]
	v_cvt_pk_bf16_f32 v192, v192, v193
	v_cvt_pk_bf16_f32 v193, v194, v195
	v_cvt_pk_bf16_f32 v194, v196, v197
	v_cvt_pk_bf16_f32 v195, v198, v199
	s_add_i32 s22, s36, 3
	s_mul_i32 s22, s22, 0x58000
	s_add_i32 s22, s22, 0x1600
	v_add_u32_e32 v232, s22, v183
	global_store_dwordx4 v232, v[192:195], s[20:21]
	s_nop 1
	s_branch .LBB0_122
